# SWA main loop hand-written: one barrier per tile, per-wave skipping of tiles fully outside the window, window mask only on boundary tiles
# speedup vs baseline: 1.0169x; 1.0037x over previous
.LBB0_741:
	v_mov_b32_e32 v159, v117
	v_exp_f32_e32 v32, v48
	v_exp_f32_e32 v33, v49
	v_exp_f32_e32 v34, v34
	v_exp_f32_e32 v35, v35
	v_exp_f32_e32 v36, v36
	v_exp_f32_e32 v37, v37
	v_exp_f32_e32 v38, v38
	v_exp_f32_e32 v39, v39
	v_exp_f32_e32 v40, v40
	v_exp_f32_e32 v41, v41
	v_exp_f32_e32 v42, v42
	v_exp_f32_e32 v43, v43
	v_exp_f32_e32 v44, v44
	v_exp_f32_e32 v45, v45
	v_exp_f32_e32 v46, v46
	v_exp_f32_e32 v47, v47
	v_add_f32_e32 v155, 0, v63
	v_add_f32_e32 v155, v82, v155
	v_add_f32_e32 v155, v61, v155
	v_add_f32_e32 v155, v81, v155
	v_add_f32_e32 v155, v59, v155
	v_add_f32_e32 v155, v62, v155
	v_add_f32_e32 v155, v58, v155
	v_add_f32_e32 v155, v60, v155
	v_add_f32_e32 v155, v55, v155
	v_add_f32_e32 v155, v57, v155
	v_add_f32_e32 v155, v53, v155
	v_add_f32_e32 v155, v56, v155
	v_add_f32_e32 v155, v51, v155
	v_add_f32_e32 v155, v54, v155
	v_add_f32_e32 v155, v50, v155
	v_add_f32_e32 v155, v52, v155
	v_add_f32_e32 v155, v32, v155
	v_add_f32_e32 v155, v33, v155
	v_add_f32_e32 v155, v34, v155
	v_add_f32_e32 v155, v35, v155
	v_add_f32_e32 v155, v36, v155
	v_add_f32_e32 v155, v37, v155
	v_add_f32_e32 v155, v38, v155
	v_add_f32_e32 v155, v39, v155
	v_add_f32_e32 v155, v40, v155
	v_add_f32_e32 v155, v41, v155
	v_add_f32_e32 v155, v42, v155
	v_add_f32_e32 v155, v43, v155
	v_add_f32_e32 v155, v44, v155
	v_add_f32_e32 v155, v45, v155
	v_add_f32_e32 v155, v46, v155
	v_add_f32_e32 v155, v47, v155
	v_mov_b32_e32 v156, v155
	v_cvt_pk_bf16_f32 v80, v63, v82
	v_cvt_pk_bf16_f32 v81, v61, v81
	v_cvt_pk_bf16_f32 v82, v59, v62
	v_cvt_pk_bf16_f32 v83, v58, v60
	v_cvt_pk_bf16_f32 v84, v55, v57
	v_cvt_pk_bf16_f32 v85, v53, v56
	v_cvt_pk_bf16_f32 v86, v51, v54
	v_cvt_pk_bf16_f32 v87, v50, v52
	v_cvt_pk_bf16_f32 v88, v32, v33
	v_cvt_pk_bf16_f32 v89, v34, v35
	v_cvt_pk_bf16_f32 v90, v36, v37
	v_cvt_pk_bf16_f32 v91, v38, v39
	v_cvt_pk_bf16_f32 v92, v40, v41
	v_cvt_pk_bf16_f32 v93, v42, v43
	v_cvt_pk_bf16_f32 v94, v44, v45
	v_cvt_pk_bf16_f32 v95, v46, v47
	v_permlane32_swap_b32_e32 v155, v156
	v_add_f32_e32 v157, v155, v156
	v_fma_f32 v108, v114, v108, v157
	v_permlane32_swap_b32_e32 v80, v82
	v_permlane32_swap_b32_e32 v81, v83
	v_permlane32_swap_b32_e32 v84, v86
	v_permlane32_swap_b32_e32 v85, v87
	v_permlane32_swap_b32_e32 v88, v90
	v_permlane32_swap_b32_e32 v89, v91
	v_permlane32_swap_b32_e32 v92, v94
	v_permlane32_swap_b32_e32 v93, v95
	ds_read_b64_tr_b16 v[120:121], v109 offset:0
	ds_read_b64_tr_b16 v[122:123], v109 offset:1024
	ds_read_b64_tr_b16 v[124:125], v109 offset:2048
	ds_read_b64_tr_b16 v[126:127], v109 offset:3072
	ds_read_b64_tr_b16 v[128:129], v109 offset:4096
	ds_read_b64_tr_b16 v[130:131], v109 offset:5120
	ds_read_b64_tr_b16 v[132:133], v109 offset:6144
	ds_read_b64_tr_b16 v[134:135], v109 offset:7168
	ds_read_b64_tr_b16 v[136:137], v109 offset:512
	ds_read_b64_tr_b16 v[138:139], v109 offset:1536
	ds_read_b64_tr_b16 v[140:141], v109 offset:2560
	ds_read_b64_tr_b16 v[142:143], v109 offset:3584
	ds_read_b64_tr_b16 v[144:145], v109 offset:4608
	ds_read_b64_tr_b16 v[146:147], v109 offset:5632
	ds_read_b64_tr_b16 v[148:149], v109 offset:6656
	ds_read_b64_tr_b16 v[150:151], v109 offset:7680
	s_waitcnt lgkmcnt(0)
	v_mfma_f32_32x32x16_bf16 v[16:31], v[80:83], v[120:123], v[16:31]
	v_mfma_f32_32x32x16_bf16 v[16:31], v[84:87], v[124:127], v[16:31]
	v_mfma_f32_32x32x16_bf16 v[16:31], v[88:91], v[128:131], v[16:31]
	v_mfma_f32_32x32x16_bf16 v[16:31], v[92:95], v[132:135], v[16:31]
	v_mfma_f32_32x32x16_bf16 v[0:15], v[80:83], v[136:139], v[0:15]
	v_mfma_f32_32x32x16_bf16 v[0:15], v[84:87], v[140:143], v[0:15]
	v_mfma_f32_32x32x16_bf16 v[0:15], v[88:91], v[144:147], v[0:15]
	v_mfma_f32_32x32x16_bf16 v[0:15], v[92:95], v[148:151], v[0:15]
	s_waitcnt vmcnt(0) lgkmcnt(0)
	s_barrier
.Lswa_loop:
	s_cmp_ge_u32 s54, s31
	s_cbranch_scc1 .Lswa_nodma_o
	s_cmp_lt_u32 s54, 4
	s_cselect_b32 s0, 0, -4
	s_cselect_b32 s1, s45, s44
	s_add_i32 s0, s0, s54
	s_lshl_b32 s0, s0, 6
	s_add_i32 s0, s0, s1
	s_mul_hi_i32 s19, s0, 0xc00
	s_mul_i32 s18, s0, 0xc00
	s_mov_b32 m0, s49
	v_lshl_add_u64 v[250:251], s[18:19], 1, v[98:99]
	global_load_lds_dwordx4 v[250:251], off
	s_mov_b32 m0, s7
	v_lshl_add_u64 v[250:251], s[18:19], 1, v[100:101]
	global_load_lds_dwordx4 v[250:251], off
.Lswa_nodma_o:
	s_mov_b32 s16, 0
	s_and_b64 vcc, exec, s[12:13]
	s_cbranch_vccnz .Lswa_full_o
	s_add_i32 s51, s54, -1
	s_cmp_lt_u32 s51, 4
	s_cbranch_scc1 .Lswa_full_o
	v_readfirstlane_b32 s10, v159
	s_nop 3
	s_cmp_lt_i32 s10, 0xfffffec0
	s_cbranch_scc1 .Lswa_end_o
	s_cmp_gt_i32 s10, 30
	s_cbranch_scc1 .Lswa_end_o
	s_cmp_lt_i32 s10, 0xffffff1e
	s_cselect_b32 s16, 1, 0
	s_cmp_gt_i32 s10, 0xffffffc0
	s_cselect_b32 s16, 1, s16
.Lswa_full_o:
	ds_read_b128 v[120:123], v113 offset:24576
	ds_read_b128 v[124:127], v113 offset:28672
	ds_read_b128 v[128:131], v110 offset:24576
	ds_read_b128 v[132:135], v110 offset:28672
	ds_read_b128 v[136:139], v111 offset:24576
	ds_read_b128 v[140:143], v111 offset:28672
	ds_read_b128 v[144:147], v112 offset:24576
	ds_read_b128 v[148:151], v112 offset:28672
	s_waitcnt lgkmcnt(7)
	v_mfma_f32_32x32x16_bf16 v[48:63], v[120:123], v[64:67], 0
	s_waitcnt lgkmcnt(6)
	v_mfma_f32_32x32x16_bf16 v[32:47], v[124:127], v[64:67], 0
	s_waitcnt lgkmcnt(5)
	v_mfma_f32_32x32x16_bf16 v[48:63], v[128:131], v[68:71], v[48:63]
	s_waitcnt lgkmcnt(4)
	v_mfma_f32_32x32x16_bf16 v[32:47], v[132:135], v[68:71], v[32:47]
	s_waitcnt lgkmcnt(3)
	v_mfma_f32_32x32x16_bf16 v[48:63], v[136:139], v[72:75], v[48:63]
	s_waitcnt lgkmcnt(2)
	v_mfma_f32_32x32x16_bf16 v[32:47], v[140:143], v[72:75], v[32:47]
	s_waitcnt lgkmcnt(1)
	v_mfma_f32_32x32x16_bf16 v[48:63], v[144:147], v[76:79], v[48:63]
	s_waitcnt lgkmcnt(0)
	v_mfma_f32_32x32x16_bf16 v[32:47], v[148:151], v[76:79], v[32:47]
	ds_read_b64_tr_b16 v[120:121], v116 offset:0
	ds_read_b64_tr_b16 v[122:123], v116 offset:1024
	ds_read_b64_tr_b16 v[124:125], v116 offset:2048
	ds_read_b64_tr_b16 v[126:127], v116 offset:3072
	ds_read_b64_tr_b16 v[128:129], v116 offset:4096
	ds_read_b64_tr_b16 v[130:131], v116 offset:5120
	ds_read_b64_tr_b16 v[132:133], v116 offset:6144
	ds_read_b64_tr_b16 v[134:135], v116 offset:7168
	ds_read_b64_tr_b16 v[136:137], v116 offset:512
	ds_read_b64_tr_b16 v[138:139], v116 offset:1536
	ds_read_b64_tr_b16 v[140:141], v116 offset:2560
	ds_read_b64_tr_b16 v[142:143], v116 offset:3584
	ds_read_b64_tr_b16 v[144:145], v116 offset:4608
	ds_read_b64_tr_b16 v[146:147], v116 offset:5632
	ds_read_b64_tr_b16 v[148:149], v116 offset:6656
	ds_read_b64_tr_b16 v[150:151], v116 offset:7680
	s_cmp_eq_u32 s16, 0
	s_cbranch_scc1 .Lswa_nomask_o
	v_add_u32_e32 v156, 0, v159
	v_add_u32_e32 v157, 32, v159
	v_cmp_lt_u32_e32 vcc, s48, v156
	v_cmp_lt_u32_e64 s[18:19], s48, v157
	s_nop 0
	v_cndmask_b32_e32 v48, v179, v48, vcc
	v_cndmask_b32_e64 v32, v179, v32, s[18:19]
	v_add_u32_e32 v156, 1, v159
	v_add_u32_e32 v157, 33, v159
	v_cmp_lt_u32_e32 vcc, s48, v156
	v_cmp_lt_u32_e64 s[18:19], s48, v157
	s_nop 0
	v_cndmask_b32_e32 v49, v179, v49, vcc
	v_cndmask_b32_e64 v33, v179, v33, s[18:19]
	v_add_u32_e32 v156, 2, v159
	v_add_u32_e32 v157, 34, v159
	v_cmp_lt_u32_e32 vcc, s48, v156
	v_cmp_lt_u32_e64 s[18:19], s48, v157
	s_nop 0
	v_cndmask_b32_e32 v50, v179, v50, vcc
	v_cndmask_b32_e64 v34, v179, v34, s[18:19]
	v_add_u32_e32 v156, 3, v159
	v_add_u32_e32 v157, 35, v159
	v_cmp_lt_u32_e32 vcc, s48, v156
	v_cmp_lt_u32_e64 s[18:19], s48, v157
	s_nop 0
	v_cndmask_b32_e32 v51, v179, v51, vcc
	v_cndmask_b32_e64 v35, v179, v35, s[18:19]
	v_add_u32_e32 v156, 8, v159
	v_add_u32_e32 v157, 40, v159
	v_cmp_lt_u32_e32 vcc, s48, v156
	v_cmp_lt_u32_e64 s[18:19], s48, v157
	s_nop 0
	v_cndmask_b32_e32 v52, v179, v52, vcc
	v_cndmask_b32_e64 v36, v179, v36, s[18:19]
	v_add_u32_e32 v156, 9, v159
	v_add_u32_e32 v157, 41, v159
	v_cmp_lt_u32_e32 vcc, s48, v156
	v_cmp_lt_u32_e64 s[18:19], s48, v157
	s_nop 0
	v_cndmask_b32_e32 v53, v179, v53, vcc
	v_cndmask_b32_e64 v37, v179, v37, s[18:19]
	v_add_u32_e32 v156, 10, v159
	v_add_u32_e32 v157, 42, v159
	v_cmp_lt_u32_e32 vcc, s48, v156
	v_cmp_lt_u32_e64 s[18:19], s48, v157
	s_nop 0
	v_cndmask_b32_e32 v54, v179, v54, vcc
	v_cndmask_b32_e64 v38, v179, v38, s[18:19]
	v_add_u32_e32 v156, 11, v159
	v_add_u32_e32 v157, 43, v159
	v_cmp_lt_u32_e32 vcc, s48, v156
	v_cmp_lt_u32_e64 s[18:19], s48, v157
	s_nop 0
	v_cndmask_b32_e32 v55, v179, v55, vcc
	v_cndmask_b32_e64 v39, v179, v39, s[18:19]
	v_add_u32_e32 v156, 16, v159
	v_add_u32_e32 v157, 48, v159
	v_cmp_lt_u32_e32 vcc, s48, v156
	v_cmp_lt_u32_e64 s[18:19], s48, v157
	s_nop 0
	v_cndmask_b32_e32 v56, v179, v56, vcc
	v_cndmask_b32_e64 v40, v179, v40, s[18:19]
	v_add_u32_e32 v156, 17, v159
	v_add_u32_e32 v157, 49, v159
	v_cmp_lt_u32_e32 vcc, s48, v156
	v_cmp_lt_u32_e64 s[18:19], s48, v157
	s_nop 0
	v_cndmask_b32_e32 v57, v179, v57, vcc
	v_cndmask_b32_e64 v41, v179, v41, s[18:19]
	v_add_u32_e32 v156, 18, v159
	v_add_u32_e32 v157, 50, v159
	v_cmp_lt_u32_e32 vcc, s48, v156
	v_cmp_lt_u32_e64 s[18:19], s48, v157
	s_nop 0
	v_cndmask_b32_e32 v58, v179, v58, vcc
	v_cndmask_b32_e64 v42, v179, v42, s[18:19]
	v_add_u32_e32 v156, 19, v159
	v_add_u32_e32 v157, 51, v159
	v_cmp_lt_u32_e32 vcc, s48, v156
	v_cmp_lt_u32_e64 s[18:19], s48, v157
	s_nop 0
	v_cndmask_b32_e32 v59, v179, v59, vcc
	v_cndmask_b32_e64 v43, v179, v43, s[18:19]
	v_add_u32_e32 v156, 24, v159
	v_add_u32_e32 v157, 56, v159
	v_cmp_lt_u32_e32 vcc, s48, v156
	v_cmp_lt_u32_e64 s[18:19], s48, v157
	s_nop 0
	v_cndmask_b32_e32 v60, v179, v60, vcc
	v_cndmask_b32_e64 v44, v179, v44, s[18:19]
	v_add_u32_e32 v156, 25, v159
	v_add_u32_e32 v157, 57, v159
	v_cmp_lt_u32_e32 vcc, s48, v156
	v_cmp_lt_u32_e64 s[18:19], s48, v157
	s_nop 0
	v_cndmask_b32_e32 v61, v179, v61, vcc
	v_cndmask_b32_e64 v45, v179, v45, s[18:19]
	v_add_u32_e32 v156, 26, v159
	v_add_u32_e32 v157, 58, v159
	v_cmp_lt_u32_e32 vcc, s48, v156
	v_cmp_lt_u32_e64 s[18:19], s48, v157
	s_nop 0
	v_cndmask_b32_e32 v62, v179, v62, vcc
	v_cndmask_b32_e64 v46, v179, v46, s[18:19]
	v_add_u32_e32 v156, 27, v159
	v_add_u32_e32 v157, 59, v159
	v_cmp_lt_u32_e32 vcc, s48, v156
	v_cmp_lt_u32_e64 s[18:19], s48, v157
	s_nop 0
	v_cndmask_b32_e32 v63, v179, v63, vcc
	v_cndmask_b32_e64 v47, v179, v47, s[18:19]
.Lswa_nomask_o:
	v_max_f32_e32 v152, v48, v49
	v_max3_f32 v152, v152, v50, v51
	v_max3_f32 v152, v152, v52, v53
	v_max3_f32 v152, v152, v54, v55
	v_max3_f32 v152, v152, v56, v57
	v_max3_f32 v152, v152, v58, v59
	v_max3_f32 v152, v152, v60, v61
	v_max3_f32 v152, v152, v62, v63
	v_max3_f32 v152, v152, v32, v33
	v_max3_f32 v152, v152, v34, v35
	v_max3_f32 v152, v152, v36, v37
	v_max3_f32 v152, v152, v38, v39
	v_max3_f32 v152, v152, v40, v41
	v_max3_f32 v152, v152, v42, v43
	v_max3_f32 v152, v152, v44, v45
	v_max3_f32 v152, v152, v46, v47
	v_mov_b32_e32 v153, v152
	s_nop 1
	v_permlane32_swap_b32_e32 v152, v153
	v_max_f32_e32 v152, v152, v153
	v_sub_f32_e32 v153, v152, v115
	v_cmp_ge_f32_e32 vcc, s41, v153
	v_max_f32_e32 v152, v115, v152
	v_sub_f32_e32 v153, v115, v152
	v_mul_f32_e32 v153, 0x3e38aa3b, v153
	v_exp_f32_e32 v153, v153
	s_cmp_eq_u64 vcc, exec
	s_cselect_b64 s[10:11], -1, 0
	v_cndmask_b32_e64 v114, v153, 1.0, s[10:11]
	v_cndmask_b32_e64 v115, v152, v115, s[10:11]
	v_mul_f32_e32 v154, 0xbe38aa3b, v115
	v_fmamk_f32 v48, v48, 0x3e38aa3b, v154
	v_fmamk_f32 v49, v49, 0x3e38aa3b, v154
	v_fmamk_f32 v50, v50, 0x3e38aa3b, v154
	v_fmamk_f32 v51, v51, 0x3e38aa3b, v154
	v_fmamk_f32 v52, v52, 0x3e38aa3b, v154
	v_fmamk_f32 v53, v53, 0x3e38aa3b, v154
	v_fmamk_f32 v54, v54, 0x3e38aa3b, v154
	v_fmamk_f32 v55, v55, 0x3e38aa3b, v154
	v_fmamk_f32 v56, v56, 0x3e38aa3b, v154
	v_fmamk_f32 v57, v57, 0x3e38aa3b, v154
	v_fmamk_f32 v58, v58, 0x3e38aa3b, v154
	v_fmamk_f32 v59, v59, 0x3e38aa3b, v154
	v_fmamk_f32 v60, v60, 0x3e38aa3b, v154
	v_fmamk_f32 v61, v61, 0x3e38aa3b, v154
	v_fmamk_f32 v62, v62, 0x3e38aa3b, v154
	v_fmamk_f32 v63, v63, 0x3e38aa3b, v154
	v_fmamk_f32 v32, v32, 0x3e38aa3b, v154
	v_fmamk_f32 v33, v33, 0x3e38aa3b, v154
	v_fmamk_f32 v34, v34, 0x3e38aa3b, v154
	v_fmamk_f32 v35, v35, 0x3e38aa3b, v154
	v_fmamk_f32 v36, v36, 0x3e38aa3b, v154
	v_fmamk_f32 v37, v37, 0x3e38aa3b, v154
	v_fmamk_f32 v38, v38, 0x3e38aa3b, v154
	v_fmamk_f32 v39, v39, 0x3e38aa3b, v154
	v_fmamk_f32 v40, v40, 0x3e38aa3b, v154
	v_fmamk_f32 v41, v41, 0x3e38aa3b, v154
	v_fmamk_f32 v42, v42, 0x3e38aa3b, v154
	v_fmamk_f32 v43, v43, 0x3e38aa3b, v154
	v_fmamk_f32 v44, v44, 0x3e38aa3b, v154
	v_fmamk_f32 v45, v45, 0x3e38aa3b, v154
	v_fmamk_f32 v46, v46, 0x3e38aa3b, v154
	v_fmamk_f32 v47, v47, 0x3e38aa3b, v154
	v_exp_f32_e32 v48, v48
	v_exp_f32_e32 v49, v49
	v_add_f32_e32 v155, 0, v48
	v_exp_f32_e32 v50, v50
	v_add_f32_e32 v155, v49, v155
	v_exp_f32_e32 v51, v51
	v_add_f32_e32 v155, v50, v155
	v_exp_f32_e32 v52, v52
	v_add_f32_e32 v155, v51, v155
	v_exp_f32_e32 v53, v53
	v_add_f32_e32 v155, v52, v155
	v_exp_f32_e32 v54, v54
	v_add_f32_e32 v155, v53, v155
	v_exp_f32_e32 v55, v55
	v_add_f32_e32 v155, v54, v155
	v_exp_f32_e32 v56, v56
	v_add_f32_e32 v155, v55, v155
	v_exp_f32_e32 v57, v57
	v_add_f32_e32 v155, v56, v155
	v_exp_f32_e32 v58, v58
	v_add_f32_e32 v155, v57, v155
	v_exp_f32_e32 v59, v59
	v_add_f32_e32 v155, v58, v155
	v_exp_f32_e32 v60, v60
	v_add_f32_e32 v155, v59, v155
	v_exp_f32_e32 v61, v61
	v_add_f32_e32 v155, v60, v155
	v_exp_f32_e32 v62, v62
	v_add_f32_e32 v155, v61, v155
	v_exp_f32_e32 v63, v63
	v_add_f32_e32 v155, v62, v155
	v_exp_f32_e32 v32, v32
	v_add_f32_e32 v155, v63, v155
	v_exp_f32_e32 v33, v33
	v_add_f32_e32 v155, v32, v155
	v_exp_f32_e32 v34, v34
	v_add_f32_e32 v155, v33, v155
	v_exp_f32_e32 v35, v35
	v_add_f32_e32 v155, v34, v155
	v_exp_f32_e32 v36, v36
	v_add_f32_e32 v155, v35, v155
	v_exp_f32_e32 v37, v37
	v_add_f32_e32 v155, v36, v155
	v_exp_f32_e32 v38, v38
	v_add_f32_e32 v155, v37, v155
	v_exp_f32_e32 v39, v39
	v_add_f32_e32 v155, v38, v155
	v_exp_f32_e32 v40, v40
	v_add_f32_e32 v155, v39, v155
	v_exp_f32_e32 v41, v41
	v_add_f32_e32 v155, v40, v155
	v_exp_f32_e32 v42, v42
	v_add_f32_e32 v155, v41, v155
	v_exp_f32_e32 v43, v43
	v_add_f32_e32 v155, v42, v155
	v_exp_f32_e32 v44, v44
	v_add_f32_e32 v155, v43, v155
	v_exp_f32_e32 v45, v45
	v_add_f32_e32 v155, v44, v155
	v_exp_f32_e32 v46, v46
	v_add_f32_e32 v155, v45, v155
	v_exp_f32_e32 v47, v47
	v_add_f32_e32 v155, v46, v155
	s_nop 0
	v_add_f32_e32 v155, v47, v155
	v_mov_b32_e32 v156, v155
	v_cvt_pk_bf16_f32 v80, v48, v49
	v_cvt_pk_bf16_f32 v81, v50, v51
	v_cvt_pk_bf16_f32 v82, v52, v53
	v_cvt_pk_bf16_f32 v83, v54, v55
	v_cvt_pk_bf16_f32 v84, v56, v57
	v_cvt_pk_bf16_f32 v85, v58, v59
	v_cvt_pk_bf16_f32 v86, v60, v61
	v_cvt_pk_bf16_f32 v87, v62, v63
	v_cvt_pk_bf16_f32 v88, v32, v33
	v_cvt_pk_bf16_f32 v89, v34, v35
	v_cvt_pk_bf16_f32 v90, v36, v37
	v_cvt_pk_bf16_f32 v91, v38, v39
	v_cvt_pk_bf16_f32 v92, v40, v41
	v_cvt_pk_bf16_f32 v93, v42, v43
	v_cvt_pk_bf16_f32 v94, v44, v45
	v_cvt_pk_bf16_f32 v95, v46, v47
	v_permlane32_swap_b32_e32 v155, v156
	v_add_f32_e32 v157, v155, v156
	v_fma_f32 v108, v114, v108, v157
	v_permlane32_swap_b32_e32 v80, v82
	v_permlane32_swap_b32_e32 v81, v83
	v_permlane32_swap_b32_e32 v84, v86
	v_permlane32_swap_b32_e32 v85, v87
	v_permlane32_swap_b32_e32 v88, v90
	v_permlane32_swap_b32_e32 v89, v91
	v_permlane32_swap_b32_e32 v92, v94
	v_permlane32_swap_b32_e32 v93, v95
	v_cmp_gt_f32_e32 vcc, 1.0, v114
	s_cbranch_vccz .Lswa_noresc_o
	s_and_saveexec_b64 s[0:1], s[8:9]
	ds_write_b32 v107, v114 offset:32896
	s_or_b64 exec, exec, s[0:1]
	s_waitcnt lgkmcnt(0)
	v_add_u32_e32 v158, s20, v104
	ds_read_b128 v[60:63], v158 offset:32992
	ds_read_b128 v[56:59], v158 offset:32960
	ds_read_b128 v[52:55], v158 offset:32928
	ds_read_b128 v[48:51], v158 offset:32896
	s_waitcnt lgkmcnt(0)
	v_pk_mul_f32 v[28:29], v[28:29], v[60:61]
	v_pk_mul_f32 v[30:31], v[30:31], v[62:63]
	v_pk_mul_f32 v[12:13], v[12:13], v[60:61]
	v_pk_mul_f32 v[14:15], v[14:15], v[62:63]
	v_pk_mul_f32 v[24:25], v[24:25], v[56:57]
	v_pk_mul_f32 v[26:27], v[26:27], v[58:59]
	v_pk_mul_f32 v[8:9], v[8:9], v[56:57]
	v_pk_mul_f32 v[10:11], v[10:11], v[58:59]
	v_pk_mul_f32 v[20:21], v[20:21], v[52:53]
	v_pk_mul_f32 v[22:23], v[22:23], v[54:55]
	v_pk_mul_f32 v[4:5], v[4:5], v[52:53]
	v_pk_mul_f32 v[6:7], v[6:7], v[54:55]
	v_pk_mul_f32 v[16:17], v[16:17], v[48:49]
	v_pk_mul_f32 v[18:19], v[18:19], v[50:51]
	v_pk_mul_f32 v[0:1], v[0:1], v[48:49]
	v_pk_mul_f32 v[2:3], v[2:3], v[50:51]
	s_nop 1
.Lswa_noresc_o:
	s_waitcnt lgkmcnt(0)
	v_mfma_f32_32x32x16_bf16 v[16:31], v[80:83], v[120:123], v[16:31]
	v_mfma_f32_32x32x16_bf16 v[16:31], v[84:87], v[124:127], v[16:31]
	v_mfma_f32_32x32x16_bf16 v[16:31], v[88:91], v[128:131], v[16:31]
	v_mfma_f32_32x32x16_bf16 v[16:31], v[92:95], v[132:135], v[16:31]
	v_mfma_f32_32x32x16_bf16 v[0:15], v[80:83], v[136:139], v[0:15]
	v_mfma_f32_32x32x16_bf16 v[0:15], v[84:87], v[140:143], v[0:15]
	v_mfma_f32_32x32x16_bf16 v[0:15], v[88:91], v[144:147], v[0:15]
	v_mfma_f32_32x32x16_bf16 v[0:15], v[92:95], v[148:151], v[0:15]
.Lswa_end_o:
	v_add_u32_e32 v159, 64, v159
	s_add_i32 s54, s54, 1
	s_waitcnt vmcnt(0) lgkmcnt(0)
	s_barrier
	s_cmp_gt_u32 s54, s31
	s_cbranch_scc1 .Lswa_done
	s_cmp_ge_u32 s54, s31
	s_cbranch_scc1 .Lswa_nodma_e
	s_cmp_lt_u32 s54, 4
	s_cselect_b32 s0, 0, -4
	s_cselect_b32 s1, s45, s44
	s_add_i32 s0, s0, s54
	s_lshl_b32 s0, s0, 6
	s_add_i32 s0, s0, s1
	s_mul_hi_i32 s19, s0, 0xc00
	s_mul_i32 s18, s0, 0xc00
	s_mov_b32 m0, s50
	v_lshl_add_u64 v[250:251], s[18:19], 1, v[98:99]
	global_load_lds_dwordx4 v[250:251], off
	s_mov_b32 m0, s21
	v_lshl_add_u64 v[250:251], s[18:19], 1, v[100:101]
	global_load_lds_dwordx4 v[250:251], off

.Lswa_full_e:
	ds_read_b128 v[120:123], v113 offset:16384
	ds_read_b128 v[124:127], v113 offset:20480
	ds_read_b128 v[128:131], v110 offset:16384
	ds_read_b128 v[132:135], v110 offset:20480
	ds_read_b128 v[136:139], v111 offset:16384
	ds_read_b128 v[140:143], v111 offset:20480
	ds_read_b128 v[144:147], v112 offset:16384
	ds_read_b128 v[148:151], v112 offset:20480
	s_waitcnt lgkmcnt(7)
	v_mfma_f32_32x32x16_bf16 v[48:63], v[120:123], v[64:67], 0
	s_waitcnt lgkmcnt(6)
	v_mfma_f32_32x32x16_bf16 v[32:47], v[124:127], v[64:67], 0
	s_waitcnt lgkmcnt(5)
	v_mfma_f32_32x32x16_bf16 v[48:63], v[128:131], v[68:71], v[48:63]
	s_waitcnt lgkmcnt(4)
	v_mfma_f32_32x32x16_bf16 v[32:47], v[132:135], v[68:71], v[32:47]
	s_waitcnt lgkmcnt(3)
	v_mfma_f32_32x32x16_bf16 v[48:63], v[136:139], v[72:75], v[48:63]
	s_waitcnt lgkmcnt(2)
	v_mfma_f32_32x32x16_bf16 v[32:47], v[140:143], v[72:75], v[32:47]
	s_waitcnt lgkmcnt(1)
	v_mfma_f32_32x32x16_bf16 v[48:63], v[144:147], v[76:79], v[48:63]
	s_waitcnt lgkmcnt(0)
	v_mfma_f32_32x32x16_bf16 v[32:47], v[148:151], v[76:79], v[32:47]
	ds_read_b64_tr_b16 v[120:121], v109 offset:0
	ds_read_b64_tr_b16 v[122:123], v109 offset:1024
	ds_read_b64_tr_b16 v[124:125], v109 offset:2048
	ds_read_b64_tr_b16 v[126:127], v109 offset:3072
	ds_read_b64_tr_b16 v[128:129], v109 offset:4096
	ds_read_b64_tr_b16 v[130:131], v109 offset:5120
	ds_read_b64_tr_b16 v[132:133], v109 offset:6144
	ds_read_b64_tr_b16 v[134:135], v109 offset:7168
	ds_read_b64_tr_b16 v[136:137], v109 offset:512
	ds_read_b64_tr_b16 v[138:139], v109 offset:1536
	ds_read_b64_tr_b16 v[140:141], v109 offset:2560
	ds_read_b64_tr_b16 v[142:143], v109 offset:3584
	ds_read_b64_tr_b16 v[144:145], v109 offset:4608
	ds_read_b64_tr_b16 v[146:147], v109 offset:5632
	ds_read_b64_tr_b16 v[148:149], v109 offset:6656
	ds_read_b64_tr_b16 v[150:151], v109 offset:7680
	s_cmp_eq_u32 s16, 0
	s_cbranch_scc1 .Lswa_nomask_e
	v_add_u32_e32 v156, 0, v159
	v_add_u32_e32 v157, 32, v159
	v_cmp_lt_u32_e32 vcc, s48, v156
	v_cmp_lt_u32_e64 s[18:19], s48, v157
	s_nop 0
	v_cndmask_b32_e32 v48, v179, v48, vcc
	v_cndmask_b32_e64 v32, v179, v32, s[18:19]
	v_add_u32_e32 v156, 1, v159
	v_add_u32_e32 v157, 33, v159
	v_cmp_lt_u32_e32 vcc, s48, v156
	v_cmp_lt_u32_e64 s[18:19], s48, v157
	s_nop 0
	v_cndmask_b32_e32 v49, v179, v49, vcc
	v_cndmask_b32_e64 v33, v179, v33, s[18:19]
	v_add_u32_e32 v156, 2, v159
	v_add_u32_e32 v157, 34, v159
	v_cmp_lt_u32_e32 vcc, s48, v156
	v_cmp_lt_u32_e64 s[18:19], s48, v157
	s_nop 0
	v_cndmask_b32_e32 v50, v179, v50, vcc
	v_cndmask_b32_e64 v34, v179, v34, s[18:19]
	v_add_u32_e32 v156, 3, v159
	v_add_u32_e32 v157, 35, v159
	v_cmp_lt_u32_e32 vcc, s48, v156
	v_cmp_lt_u32_e64 s[18:19], s48, v157
	s_nop 0
	v_cndmask_b32_e32 v51, v179, v51, vcc
	v_cndmask_b32_e64 v35, v179, v35, s[18:19]
	v_add_u32_e32 v156, 8, v159
	v_add_u32_e32 v157, 40, v159
	v_cmp_lt_u32_e32 vcc, s48, v156
	v_cmp_lt_u32_e64 s[18:19], s48, v157
	s_nop 0
	v_cndmask_b32_e32 v52, v179, v52, vcc
	v_cndmask_b32_e64 v36, v179, v36, s[18:19]
	v_add_u32_e32 v156, 9, v159
	v_add_u32_e32 v157, 41, v159
	v_cmp_lt_u32_e32 vcc, s48, v156
	v_cmp_lt_u32_e64 s[18:19], s48, v157
	s_nop 0
	v_cndmask_b32_e32 v53, v179, v53, vcc
	v_cndmask_b32_e64 v37, v179, v37, s[18:19]
	v_add_u32_e32 v156, 10, v159
	v_add_u32_e32 v157, 42, v159
	v_cmp_lt_u32_e32 vcc, s48, v156
	v_cmp_lt_u32_e64 s[18:19], s48, v157
	s_nop 0
	v_cndmask_b32_e32 v54, v179, v54, vcc
	v_cndmask_b32_e64 v38, v179, v38, s[18:19]
	v_add_u32_e32 v156, 11, v159
	v_add_u32_e32 v157, 43, v159
	v_cmp_lt_u32_e32 vcc, s48, v156
	v_cmp_lt_u32_e64 s[18:19], s48, v157
	s_nop 0
	v_cndmask_b32_e32 v55, v179, v55, vcc
	v_cndmask_b32_e64 v39, v179, v39, s[18:19]
	v_add_u32_e32 v156, 16, v159
	v_add_u32_e32 v157, 48, v159
	v_cmp_lt_u32_e32 vcc, s48, v156
	v_cmp_lt_u32_e64 s[18:19], s48, v157
	s_nop 0
	v_cndmask_b32_e32 v56, v179, v56, vcc
	v_cndmask_b32_e64 v40, v179, v40, s[18:19]
	v_add_u32_e32 v156, 17, v159
	v_add_u32_e32 v157, 49, v159
	v_cmp_lt_u32_e32 vcc, s48, v156
	v_cmp_lt_u32_e64 s[18:19], s48, v157
	s_nop 0
	v_cndmask_b32_e32 v57, v179, v57, vcc
	v_cndmask_b32_e64 v41, v179, v41, s[18:19]
	v_add_u32_e32 v156, 18, v159
	v_add_u32_e32 v157, 50, v159
	v_cmp_lt_u32_e32 vcc, s48, v156
	v_cmp_lt_u32_e64 s[18:19], s48, v157
	s_nop 0
	v_cndmask_b32_e32 v58, v179, v58, vcc
	v_cndmask_b32_e64 v42, v179, v42, s[18:19]
	v_add_u32_e32 v156, 19, v159
	v_add_u32_e32 v157, 51, v159
	v_cmp_lt_u32_e32 vcc, s48, v156
	v_cmp_lt_u32_e64 s[18:19], s48, v157
	s_nop 0
	v_cndmask_b32_e32 v59, v179, v59, vcc
	v_cndmask_b32_e64 v43, v179, v43, s[18:19]
	v_add_u32_e32 v156, 24, v159
	v_add_u32_e32 v157, 56, v159
	v_cmp_lt_u32_e32 vcc, s48, v156
	v_cmp_lt_u32_e64 s[18:19], s48, v157
	s_nop 0
	v_cndmask_b32_e32 v60, v179, v60, vcc
	v_cndmask_b32_e64 v44, v179, v44, s[18:19]
	v_add_u32_e32 v156, 25, v159
	v_add_u32_e32 v157, 57, v159
	v_cmp_lt_u32_e32 vcc, s48, v156
	v_cmp_lt_u32_e64 s[18:19], s48, v157
	s_nop 0
	v_cndmask_b32_e32 v61, v179, v61, vcc
	v_cndmask_b32_e64 v45, v179, v45, s[18:19]
	v_add_u32_e32 v156, 26, v159
	v_add_u32_e32 v157, 58, v159
	v_cmp_lt_u32_e32 vcc, s48, v156
	v_cmp_lt_u32_e64 s[18:19], s48, v157
	s_nop 0
	v_cndmask_b32_e32 v62, v179, v62, vcc
	v_cndmask_b32_e64 v46, v179, v46, s[18:19]
	v_add_u32_e32 v156, 27, v159
	v_add_u32_e32 v157, 59, v159
	v_cmp_lt_u32_e32 vcc, s48, v156
	v_cmp_lt_u32_e64 s[18:19], s48, v157
	s_nop 0
	v_cndmask_b32_e32 v63, v179, v63, vcc
	v_cndmask_b32_e64 v47, v179, v47, s[18:19]

.Lswa_end_e:
	v_add_u32_e32 v159, 64, v159
	s_add_i32 s54, s54, 1
	s_waitcnt vmcnt(0) lgkmcnt(0)
	s_barrier
	s_cmp_le_u32 s54, s31
	s_cbranch_scc1 .Lswa_loop
.Lswa_done:
	v_mul_f32_e32 v156, 0x3fb8aa3b, v96
	v_mul_f32_e32 v157, 0x3e38aa3b, v115
	v_sub_f32_e32 v156, v156, v157
	v_exp_f32_e32 v156, v156
	v_cmp_gt_u32_e32 vcc, 32, v105
	s_nop 0
	v_add_f32_e32 v156, v156, v108
	s_nop 3
	s_and_saveexec_b64 s[0:1], vcc
	s_cbranch_execz .LBB0_730
	ds_write_b32 v107, v156 offset:32768
	s_branch .LBB0_730
